# conversion queue re-partitioned: no conversions on the top-k slow blocks, 12288 items per top-k phase on the fast blocks, lighter out1/in2 tails
# speedup vs baseline: 1.0071x; 1.0071x over previous
.LBB0_696:
	s_cmpk_lt_u32 s2, 0x80
	s_cselect_b64 s[4:5], -1, 0
	s_cmpk_gt_u32 s2, 0x7f
	s_cselect_b64 s[10:11], -1, 0
	s_movk_i32 s3, 0x4000
	s_and_b64 s[6:7], s[10:11], exec
	s_cselect_b32 s12, s3, 0x7000
	s_movk_i32 s3, 0x7000
	s_cselect_b32 s3, 0x7000, s3
	s_cmpk_eq_i32 s56, 0x100
	s_cselect_b64 s[6:7], -1, 0
	s_and_b64 s[8:9], s[6:7], exec
	s_cselect_b32 s3, s3, 0x6000
	s_cselect_b32 s18, s12, s54
	s_cmp_ge_u32 s18, s3
	s_movk_i32 s19, 0x6000
	s_waitcnt vmcnt(0)
	s_barrier
	s_cbranch_scc1 .LBB0_711
	v_readlane_b32 s8, v255, 7
	s_and_b32 s8, s8, 0x3f8
	v_readlane_b32 s13, v255, 6
	s_add_i32 s20, s13, s8
	s_lshl_b32 s21, s20, 1
	s_movk_i32 s12, 0x800
	s_and_b64 s[8:9], s[10:11], exec
	s_cselect_b32 s12, s12, 0x400
	s_and_b64 s[8:9], s[6:7], exec
	s_mul_i32 s8, s13, 0x2200
	s_cselect_b32 s22, s12, s55
	s_add_i32 s24, s8, 0
	v_cndmask_b32_e64 v2, 0, 1, s[4:5]
	v_and_b32_e32 v1, 63, v0
	s_mov_b32 s9, 0
	s_mov_b32 s23, 0x10000
	s_add_i32 s24, s24, 0x10000
	s_and_b64 s[10:11], s[10:11], s[6:7]
	v_cmp_ne_u32_e64 s[4:5], 1, v2
	v_mov_b32_e32 v3, 0
	s_movk_i32 s25, 0x2000
	s_movk_i32 s26, 0x4000
	s_mov_b32 s27, 0x8000
	s_mov_b32 s28, 0xa000
	s_mov_b32 s29, 0xc000
	s_mov_b32 s30, 0xe000
	s_mov_b32 s31, 0x12000
	s_mov_b32 s34, 0x14000
	s_mov_b32 s35, 0x16000
	s_mov_b32 s36, 0x18000
	s_mov_b32 s37, 0x1a000
	s_mov_b32 s38, 0x1c000
	s_mov_b32 s39, 0x1e000
	s_mov_b32 s41, 0x20000
	s_mov_b32 s42, 0x22000
	s_mov_b32 s43, 0x24000
	s_mov_b32 s45, 0x26000
	s_mov_b32 s46, 0x28000
	s_mov_b32 s47, 0x2a000
	s_mov_b32 s49, 0x2c000
	s_mov_b32 s50, 0x2e000
	s_mov_b32 s51, 0x30000
	s_mov_b32 s57, 0x32000
	s_mov_b32 s58, 0x34000
	s_mov_b32 s59, 0x36000
	s_mov_b32 s72, 0x38000
	s_mov_b32 s73, 0x3a000
	s_mov_b32 s78, 0x3c000
	s_mov_b32 s79, 0x3e000
	s_movk_i32 s86, 0x84
	s_branch .LBB0_699

.LBB0_1002:
	s_cmp_gt_i32 s60, 14
	s_cbranch_scc1 .LBB0_1075
	s_cmpk_lg_i32 s56, 0x100
	s_cselect_b64 s[4:5], -1, 0
	s_cmpk_lt_i32 s2, 0x60
	s_cselect_b64 s[6:7], -1, 0
	s_or_b64 s[4:5], s[6:7], s[4:5]
	s_and_b64 vcc, exec, s[4:5]
	s_cbranch_vccnz .LBB0_1011
	s_add_i32 s3, s54, 0x6d00
	s_cmp_gt_i32 s3, 0x97ff
	s_cbranch_scc1 .LBB0_1011
	v_readlane_b32 s4, v255, 6
	s_mulk_i32 s4, 0x2200
	s_add_i32 s11, s4, 0
	v_and_b32_e32 v1, 63, v0
	s_mov_b32 s5, 0
	s_mov_b32 s10, 0x10000
	s_add_i32 s11, s11, 0x10000
	s_lshl_b32 s12, s3, 1
	s_lshl_b32 s13, s3, 5
	s_mov_b32 s14, 0x7b00000
	s_waitcnt vmcnt(0)
	v_mov_b32_e32 v3, 0
	s_movk_i32 s15, 0x2000
	s_movk_i32 s16, 0x4000
	s_movk_i32 s17, 0x6000
	s_mov_b32 s18, 0x8000
	s_mov_b32 s19, 0xa000
	s_mov_b32 s20, 0xc000
	s_mov_b32 s21, 0xe000
	s_mov_b32 s22, 0x12000
	s_mov_b32 s23, 0x14000
	s_mov_b32 s24, 0x16000
	s_mov_b32 s25, 0x18000
	s_mov_b32 s26, 0x1a000
	s_mov_b32 s27, 0x1c000
	s_mov_b32 s28, 0x1e000
	s_mov_b32 s29, 0x20000
	s_mov_b32 s30, 0x22000
	s_mov_b32 s31, 0x24000
	s_mov_b32 s34, 0x26000
	s_mov_b32 s35, 0x28000
	s_mov_b32 s36, 0x2a000
	s_mov_b32 s37, 0x2c000
	s_mov_b32 s38, 0x2e000
	s_mov_b32 s39, 0x30000
	s_mov_b32 s41, 0x32000
	s_mov_b32 s42, 0x34000
	s_mov_b32 s43, 0x36000
	s_mov_b32 s45, 0x38000
	s_mov_b32 s46, 0x3a000
	s_mov_b32 s47, 0x3c000
	s_mov_b32 s49, 0x3e000
	s_movk_i32 s50, 0x84
	s_mov_b32 s51, 0x4b00000
	s_movk_i32 s57, 0xc8
	s_branch .LBB0_1007
.LBB0_1006:
	s_add_i32 s4, s3, 0x500
	s_addk_i32 s12, 0xa00
	s_add_i32 s13, s13, 0xa000
	s_cmp_lt_i32 s3, 0x9300
	s_mov_b32 s3, s4
	s_cbranch_scc0 .LBB0_1011

.LBB0_1314:
	s_cmp_gt_i32 s60, 18
	s_cselect_b64 s[4:5], -1, 0
	s_cmp_lt_i32 s61, 19
	s_cselect_b64 s[6:7], -1, 0
	s_or_b64 s[4:5], s[4:5], s[6:7]
	s_and_b64 vcc, exec, s[4:5]
	s_cbranch_vccnz .LBB0_1390
	s_cmpk_lg_i32 s56, 0x100
	s_cselect_b64 s[4:5], -1, 0
	s_cmp_lt_i32 s2, 32
	s_cselect_b64 s[6:7], -1, 0
	s_or_b64 s[4:5], s[6:7], s[4:5]
	s_and_b64 vcc, exec, s[4:5]
	s_cbranch_vccnz .LBB0_1323
	s_add_i32 s3, s54, 0x9700
	s_cmp_gt_i32 s3, 0xbfff
	s_cbranch_scc1 .LBB0_1323
	v_readlane_b32 s4, v255, 6
	s_mulk_i32 s4, 0x2200
	s_add_i32 s11, s4, 0
	v_and_b32_e32 v1, 63, v0
	s_mov_b32 s5, 0
	s_mov_b32 s10, 0x10000
	s_add_i32 s11, s11, 0x10000
	s_lshl_b32 s12, s3, 1
	s_lshl_b32 s13, s3, 5
	s_mov_b32 s14, 0x7b00000
	s_waitcnt vmcnt(0)
	v_mov_b32_e32 v3, 0
	s_movk_i32 s15, 0x2000
	s_movk_i32 s16, 0x4000
	s_movk_i32 s17, 0x6000
	s_mov_b32 s18, 0x8000
	s_mov_b32 s19, 0xa000
	s_mov_b32 s20, 0xc000
	s_mov_b32 s21, 0xe000
	s_mov_b32 s22, 0x12000
	s_mov_b32 s23, 0x14000
	s_mov_b32 s24, 0x16000
	s_mov_b32 s25, 0x18000
	s_mov_b32 s26, 0x1a000
	s_mov_b32 s27, 0x1c000
	s_mov_b32 s28, 0x1e000
	s_mov_b32 s29, 0x20000
	s_mov_b32 s30, 0x22000
	s_mov_b32 s31, 0x24000
	s_mov_b32 s34, 0x26000
	s_mov_b32 s35, 0x28000
	s_mov_b32 s36, 0x2a000
	s_mov_b32 s37, 0x2c000
	s_mov_b32 s38, 0x2e000
	s_mov_b32 s39, 0x30000
	s_mov_b32 s41, 0x32000
	s_mov_b32 s42, 0x34000
	s_mov_b32 s43, 0x36000
	s_mov_b32 s45, 0x38000
	s_mov_b32 s46, 0x3a000
	s_mov_b32 s47, 0x3c000
	s_mov_b32 s49, 0x3e000
	s_movk_i32 s50, 0x84
	s_mov_b32 s51, 0x4b00000
	s_movk_i32 s57, 0xc8
	s_branch .LBB0_1319

.LBB0_1580:
	s_cmpk_lt_u32 s2, 0x80
	s_cselect_b64 s[4:5], -1, 0
	s_cmpk_gt_u32 s2, 0x7f
	s_cselect_b64 s[10:11], -1, 0
	s_mov_b32 s3, 0xc000
	s_and_b64 s[6:7], s[10:11], exec
	s_cselect_b32 s12, s3, 0xf000
	s_add_i32 s13, s54, 0x6000
	s_cmpk_eq_i32 s56, 0x100
	s_cselect_b64 s[6:7], -1, 0
	s_mov_b32 s18, 0xc000
	s_and_b64 s[8:9], s[6:7], exec
	s_cselect_b32 s19, 0xf000, s18
	s_cselect_b32 s20, s12, s13
	s_movk_i32 s3, 0x6000
	s_cmp_ge_u32 s20, s19
	s_waitcnt vmcnt(0)
	s_barrier
	s_cbranch_scc1 .LBB0_1595
	v_readlane_b32 s8, v255, 7
	s_and_b32 s8, s8, 0x3f8
	v_readlane_b32 s13, v255, 6
	s_add_i32 s21, s13, s8
	s_lshl_b32 s22, s21, 1
	s_movk_i32 s12, 0x800
	s_and_b64 s[8:9], s[10:11], exec
	s_cselect_b32 s12, s12, 0x400
	s_and_b64 s[8:9], s[6:7], exec
	s_mul_i32 s8, s13, 0x2200
	s_cselect_b32 s23, s12, s55
	s_add_i32 s25, s8, 0
	v_cndmask_b32_e64 v2, 0, 1, s[4:5]
	v_and_b32_e32 v1, 63, v0
	s_mov_b32 s9, 0
	s_mov_b32 s24, 0x10000
	s_add_i32 s25, s25, 0x10000
	s_and_b64 s[10:11], s[10:11], s[6:7]
	v_cmp_ne_u32_e64 s[4:5], 1, v2
	v_mov_b32_e32 v3, 0
	s_movk_i32 s26, 0x2000
	s_movk_i32 s27, 0x4000
	s_mov_b32 s28, 0x8000
	s_mov_b32 s29, 0xa000
	s_mov_b32 s30, 0xe000
	s_mov_b32 s31, 0x12000
	s_mov_b32 s34, 0x14000
	s_mov_b32 s35, 0x16000
	s_mov_b32 s36, 0x18000
	s_mov_b32 s37, 0x1a000
	s_mov_b32 s38, 0x1c000
	s_mov_b32 s39, 0x1e000
	s_mov_b32 s41, 0x20000
	s_mov_b32 s42, 0x22000
	s_mov_b32 s43, 0x24000
	s_mov_b32 s45, 0x26000
	s_mov_b32 s46, 0x28000
	s_mov_b32 s47, 0x2a000
	s_mov_b32 s49, 0x2c000
	s_mov_b32 s57, 0x2e000
	s_mov_b32 s58, 0x30000
	s_mov_b32 s59, 0x32000
	s_mov_b32 s72, 0x34000
	s_mov_b32 s73, 0x36000
	s_mov_b32 s78, 0x38000
	s_mov_b32 s79, 0x3a000
	s_mov_b32 s84, 0x3c000
	s_mov_b32 s85, 0x3e000
	s_movk_i32 s86, 0x84
	s_branch .LBB0_1583

.LBB0_1885:
	s_cmp_lt_i32 s61, 27
	s_cbranch_scc1 .LBB0_2670
	s_cmp_gt_i32 s60, 26
	s_cbranch_scc1 .LBB0_1959
	s_cmpk_lg_i32 s56, 0x100
	s_cselect_b64 s[4:5], -1, 0
	s_cmp_lt_i32 s2, 48
	s_cselect_b64 s[6:7], -1, 0
	s_or_b64 s[4:5], s[6:7], s[4:5]
	s_and_b64 vcc, exec, s[4:5]
	s_cbranch_vccnz .LBB0_1895
	s_add_i32 s3, s54, 0xee80
	s_cmp_gt_i32 s3, 0x11fff
	s_cbranch_scc1 .LBB0_1895
	v_readlane_b32 s4, v255, 6
	s_mulk_i32 s4, 0x2200
	s_add_i32 s11, s4, 0
	v_and_b32_e32 v1, 63, v0
	s_mov_b32 s5, 0
	s_mov_b32 s10, 0x10000
	s_add_i32 s11, s11, 0x10000
	s_lshl_b32 s12, s3, 1
	s_lshl_b32 s13, s3, 5
	s_waitcnt vmcnt(0)
	v_mov_b32_e32 v3, 0
	s_movk_i32 s14, 0x2000
	s_movk_i32 s15, 0x4000
	s_movk_i32 s16, 0x6000
	s_mov_b32 s17, 0x8000
	s_mov_b32 s18, 0xa000
	s_mov_b32 s19, 0xc000
	s_mov_b32 s20, 0xe000
	s_mov_b32 s21, 0x12000
	s_mov_b32 s22, 0x14000
	s_mov_b32 s23, 0x16000
	s_mov_b32 s24, 0x18000
	s_mov_b32 s25, 0x1a000
	s_mov_b32 s26, 0x1c000
	s_mov_b32 s27, 0x1e000
	s_mov_b32 s28, 0x20000
	s_mov_b32 s29, 0x22000
	s_mov_b32 s30, 0x24000
	s_mov_b32 s31, 0x26000
	s_mov_b32 s34, 0x28000
	s_mov_b32 s35, 0x2a000
	s_mov_b32 s36, 0x2c000
	s_mov_b32 s37, 0x2e000
	s_mov_b32 s38, 0x30000
	s_mov_b32 s39, 0x32000
	s_mov_b32 s41, 0x34000
	s_mov_b32 s42, 0x36000
	s_mov_b32 s43, 0x38000
	s_mov_b32 s45, 0x3a000
	s_mov_b32 s46, 0x3c000
	s_mov_b32 s47, 0x3e000
	s_movk_i32 s49, 0x84
	s_movk_i32 s50, 0xc8
	s_branch .LBB0_1891
.LBB0_1890:
	s_add_i32 s4, s3, 0x680
	s_addk_i32 s12, 0xd00
	s_add_i32 s13, s13, 0xd000
	s_cmp_lt_i32 s3, 0x11980
	s_mov_b32 s3, s4
	s_cbranch_scc0 .LBB0_1895

.LBB0_2349:
	s_cmpk_lt_u32 s2, 0x80
	s_cselect_b64 s[4:5], -1, 0
	s_cmpk_gt_u32 s2, 0x7f
	s_cselect_b64 s[10:11], -1, 0
	s_mov_b32 s3, 0x12000
	s_and_b64 s[6:7], s[10:11], exec
	s_cselect_b32 s12, s3, 0x15000
	s_mov_b32 s3, 0x15000
	s_cselect_b32 s13, 0x15000, s3
	s_add_i32 s14, s54, 0xc000
	s_cmpk_eq_i32 s56, 0x100
	s_cselect_b64 s[6:7], -1, 0
	s_and_b64 s[8:9], s[6:7], exec
	s_cselect_b32 s18, s13, 0x12000
	s_cselect_b32 s19, s12, s14
	s_mov_b32 s3, 0xc000
	s_cmp_ge_u32 s19, s18
	s_mov_b32 s20, 0x12000
	s_waitcnt vmcnt(0)
	s_barrier
	s_cbranch_scc1 .LBB0_2364
	v_readlane_b32 s8, v255, 7
	s_and_b32 s8, s8, 0x3f8
	v_readlane_b32 s13, v255, 6
	s_add_i32 s21, s13, s8
	s_lshl_b32 s22, s21, 1
	s_movk_i32 s12, 0x800
	s_and_b64 s[8:9], s[10:11], exec
	s_cselect_b32 s12, s12, 0x400
	s_and_b64 s[8:9], s[6:7], exec
	s_mul_i32 s8, s13, 0x2200
	s_cselect_b32 s23, s12, s55
	s_add_i32 s25, s8, 0
	v_cndmask_b32_e64 v2, 0, 1, s[4:5]
	v_and_b32_e32 v1, 63, v0
	s_mov_b32 s9, 0
	s_mov_b32 s24, 0x10000
	s_add_i32 s25, s25, 0x10000
	s_and_b64 s[10:11], s[10:11], s[6:7]
	v_cmp_ne_u32_e64 s[4:5], 1, v2
	v_mov_b32_e32 v3, 0
	s_movk_i32 s26, 0x2000
	s_movk_i32 s27, 0x4000
	s_movk_i32 s28, 0x6000
	s_mov_b32 s29, 0x8000
	s_mov_b32 s30, 0xa000
	s_mov_b32 s31, 0xe000
	s_mov_b32 s34, 0x14000
	s_mov_b32 s35, 0x16000
	s_mov_b32 s36, 0x18000
	s_mov_b32 s37, 0x1a000
	s_mov_b32 s38, 0x1c000
	s_mov_b32 s39, 0x1e000
	s_mov_b32 s41, 0x20000
	s_mov_b32 s42, 0x22000
	s_mov_b32 s43, 0x24000
	s_mov_b32 s45, 0x26000
	s_mov_b32 s46, 0x28000
	s_mov_b32 s47, 0x2a000
	s_mov_b32 s49, 0x2c000
	s_mov_b32 s57, 0x2e000
	s_mov_b32 s58, 0x30000
	s_mov_b32 s59, 0x32000
	s_mov_b32 s72, 0x34000
	s_mov_b32 s73, 0x36000
	s_mov_b32 s78, 0x38000
	s_mov_b32 s79, 0x3a000
	s_mov_b32 s84, 0x3c000
	s_mov_b32 s85, 0x3e000
	s_movk_i32 s86, 0x84
	s_branch .LBB0_2352

.LBB0_3025:
	s_cmpk_lt_u32 s2, 0x80
	s_cselect_b64 s[4:5], -1, 0
	s_cmpk_gt_u32 s2, 0x7f
	s_cselect_b64 s[10:11], -1, 0
	s_mov_b32 s3, 0x15000
	s_and_b64 s[6:7], s[10:11], exec
	s_cselect_b32 s12, s3, 0x18000
	s_add_i32 s13, s54, 0x12000
	s_cmpk_eq_i32 s56, 0x100
	s_cselect_b64 s[6:7], -1, 0
	s_and_b64 s[8:9], s[6:7], exec
	s_cselect_b32 s18, s12, s13
	s_and_b64 s[8:9], s[10:11], s[6:7]
	s_mov_b32 s19, 0x18000
	s_and_b64 s[12:13], s[8:9], exec
	s_cselect_b32 s20, 0x18000, s19
	s_mov_b32 s3, 0x12000
	s_cmp_ge_u32 s18, s20
	s_waitcnt vmcnt(0)
	s_barrier
	s_cbranch_scc1 .LBB0_3040
	v_readlane_b32 s12, v255, 7
	s_and_b32 s12, s12, 0x3f8
	v_readlane_b32 s13, v255, 6
	s_add_i32 s21, s13, s12
	s_lshl_b32 s22, s21, 1
	s_movk_i32 s12, 0x800
	s_and_b64 s[10:11], s[10:11], exec
	s_cselect_b32 s12, s12, 0x400
	s_and_b64 s[10:11], s[6:7], exec
	s_mul_i32 s10, s13, 0x2200
	s_cselect_b32 s23, s12, s55
	s_add_i32 s25, s10, 0
	v_cndmask_b32_e64 v2, 0, 1, s[4:5]
	s_mov_b32 s11, 0
	s_mov_b32 s24, 0x10000
	s_add_i32 s25, s25, 0x10000
	v_cmp_ne_u32_e64 s[4:5], 1, v2
	v_mov_b32_e32 v3, 0
	s_movk_i32 s26, 0x2000
	s_movk_i32 s27, 0x4000
	s_movk_i32 s28, 0x6000
	s_mov_b32 s29, 0x8000
	s_mov_b32 s30, 0xa000
	s_mov_b32 s31, 0xc000
	s_mov_b32 s34, 0xe000
	s_mov_b32 s35, 0x14000
	s_mov_b32 s36, 0x16000
	s_mov_b32 s37, 0x1a000
	s_mov_b32 s38, 0x1c000
	s_mov_b32 s39, 0x1e000
	s_mov_b32 s41, 0x20000
	s_mov_b32 s42, 0x22000
	s_mov_b32 s43, 0x24000
	s_mov_b32 s45, 0x26000
	s_mov_b32 s46, 0x28000
	s_mov_b32 s47, 0x2a000
	s_mov_b32 s50, 0x2c000
	s_mov_b32 s51, 0x2e000
	s_mov_b32 s57, 0x30000
	s_mov_b32 s58, 0x32000
	s_mov_b32 s59, 0x34000
	s_mov_b32 s72, 0x36000
	s_mov_b32 s73, 0x38000
	s_mov_b32 s76, 0x3a000
	s_mov_b32 s77, 0x3c000
	s_mov_b32 s78, 0x3e000
	s_movk_i32 s79, 0x84
	s_movk_i32 s80, 0xc8
	s_branch .LBB0_3028
